# epilogue de-serialisation: the attention pass epilogue's gate-tile loads are issued before the trailing context steps (into the dead bias-row registers), no load latency at the pass boundary
# speedup vs baseline: 1.0095x; 1.0095x over previous
.LBB0_450:
	v_mov_b32_e32 v1, v226
	v_mov_b32_e32 v3, s73
	s_waitcnt vmcnt(1)
	v_and_or_b32 v8, v1, 15, s69
	v_ashrrev_i32_e32 v1, 1, v1
	s_waitcnt vmcnt(0)
	v_and_b32_e32 v4, -8, v1
	v_or_b32_e32 v2, s74, v8
	v_ashrrev_i32_e32 v5, 31, v4
	v_lshlrev_b64 v[18:19], 1, v[4:5]
	v_lshl_add_u64 v[6:7], v[2:3], 0, s[36:37]
	v_lshl_add_u64 v[4:5], s[46:47], 0, v[18:19]
	v_lshlrev_b64 v[6:7], 10, v[6:7]
	v_lshl_add_u64 v[6:7], v[4:5], 0, v[6:7]
	v_mov_b32_e32 v1, v222
	s_ashr_i32 s59, s58, 31
	s_nop 0
	v_permlane16_swap_b32_e32 v222, v1
	s_lshl_b64 s[0:1], s[58:59], 12
	v_add_f32_e32 v1, v222, v1
	v_or_b32_e32 v40, s0, v8
	v_mov_b32_e32 v10, v1
	v_mov_b32_e32 v21, s1
	v_lshl_add_u64 v[6:7], v[2:3], 0, s[54:55]
	v_lshl_add_u64 v[8:9], v[2:3], 0, s[50:51]
	v_lshl_add_u64 v[2:3], v[2:3], 0, s[56:57]
	v_permlane32_swap_b32_e32 v1, v10
	v_or_b32_e32 v20, s36, v40
	v_lshlrev_b64 v[6:7], 10, v[6:7]
	v_lshlrev_b64 v[8:9], 10, v[8:9]
	v_lshlrev_b64 v[2:3], 10, v[2:3]
	v_add_f32_e32 v1, v1, v10
	v_lshlrev_b64 v[10:11], 11, v[20:21]
	v_lshl_add_u64 v[10:11], s[48:49], 0, v[10:11]
	v_lshl_add_u64 v[6:7], v[4:5], 0, v[6:7]
	v_lshl_add_u64 v[8:9], v[4:5], 0, v[8:9]
	v_lshl_add_u64 v[2:3], v[4:5], 0, v[2:3]
	v_lshl_add_u64 v[38:39], v[10:11], 0, v[18:19]
	s_nop 0
	s_nop 0
	v_mov_b32_e32 v22, v204
	v_mov_b32_e32 v23, v205
	v_mov_b32_e32 v24, v206
	v_mov_b32_e32 v25, v207
	v_mov_b32_e32 v26, v208
	v_mov_b32_e32 v27, v209
	v_mov_b32_e32 v28, v210
	v_mov_b32_e32 v29, v211
	v_mov_b32_e32 v30, v212
	v_mov_b32_e32 v31, v213
	v_mov_b32_e32 v32, v214
	v_mov_b32_e32 v33, v215
	v_mov_b32_e32 v34, v242
	v_mov_b32_e32 v35, v243
	v_mov_b32_e32 v36, v244
	v_mov_b32_e32 v37, v245
	v_mov_b32_e32 v14, v180
	v_mov_b32_e32 v15, v181
	v_mov_b32_e32 v16, v182
	v_mov_b32_e32 v17, v183
	v_mov_b32_e32 v10, v184
	v_mov_b32_e32 v11, v185
	v_mov_b32_e32 v12, v186
	v_mov_b32_e32 v13, v187
	v_mov_b32_e32 v6, v80
	v_mov_b32_e32 v7, v81
	v_mov_b32_e32 v8, v82
	v_mov_b32_e32 v9, v83
	v_mov_b32_e32 v2, v84
	v_mov_b32_e32 v3, v85
	v_mov_b32_e32 v4, v86
	v_mov_b32_e32 v5, v87
	v_div_scale_f32 v20, s[0:1], v1, v1, 1.0
	v_rcp_f32_e32 v42, v20
	v_div_scale_f32 v41, vcc, 1.0, v1, 1.0
	s_add_i32 s71, s71, 1
	v_fma_f32 v43, -v20, v42, 1.0
	v_fmac_f32_e32 v42, v43, v42
	v_mul_f32_e32 v43, v41, v42
	v_fma_f32 v44, -v20, v43, v41
	v_fmac_f32_e32 v43, v44, v42
	v_fma_f32 v20, -v20, v43, v41
	v_div_fmas_f32 v20, v20, v42, v43
	v_div_fixup_f32 v1, v20, v1, 1.0
	v_mul_f32_e32 v20, v96, v1
	v_mul_f32_e32 v41, v97, v1
	v_mul_f32_e32 v43, v99, v1
	v_mul_f32_e32 v42, v98, v1
	v_mul_f32_e32 v45, v89, v1
	v_mul_f32_e32 v47, v91, v1
	v_mul_f32_e32 v48, v72, v1
	v_mul_f32_e32 v49, v73, v1
	v_mul_f32_e32 v44, v88, v1
	v_mul_f32_e32 v46, v90, v1
	s_waitcnt vmcnt(7)
	v_lshlrev_b32_e32 v50, 16, v22
	v_and_b32_e32 v22, 0xffff0000, v22
	v_lshlrev_b32_e32 v51, 16, v23
	v_and_b32_e32 v23, 0xffff0000, v23
	v_mul_f32_e32 v20, v20, v50
	v_mul_f32_e32 v22, v41, v22
	v_lshlrev_b32_e32 v72, 16, v24
	v_and_b32_e32 v24, 0xffff0000, v24
	v_lshlrev_b32_e32 v73, 16, v25
	v_and_b32_e32 v25, 0xffff0000, v25
	s_waitcnt vmcnt(6)
	v_lshlrev_b32_e32 v76, 16, v26
	v_mul_f32_e32 v23, v43, v23
	v_cvt_pk_bf16_f32 v22, v20, v22
	v_and_b32_e32 v20, 0xffff0000, v26
	v_mov_b32_e32 v26, v223
	v_mul_f32_e32 v41, v42, v51
	v_mul_f32_e32 v24, v45, v24
	v_mul_f32_e32 v25, v47, v25
	v_cvt_pk_bf16_f32 v23, v41, v23
	v_mul_f32_e32 v20, v49, v20
	v_permlane16_swap_b32_e32 v223, v26
	v_mul_f32_e32 v42, v44, v72
	v_mul_f32_e32 v43, v46, v73
	v_mul_f32_e32 v44, v48, v76
	v_cvt_pk_bf16_f32 v24, v42, v24
	v_cvt_pk_bf16_f32 v25, v43, v25
	global_store_dwordx4 v[38:39], v[22:25], off offset:1024
	v_add_f32_e32 v26, v223, v26
	s_nop 0
	v_cvt_pk_bf16_f32 v22, v44, v20
	v_mul_f32_e32 v20, v74, v1
	v_lshlrev_b32_e32 v23, 16, v27
	v_mul_f32_e32 v20, v20, v23
	v_mul_f32_e32 v23, v75, v1
	v_and_b32_e32 v24, 0xffff0000, v27
	v_mov_b32_e32 v27, v26
	v_mul_f32_e32 v23, v23, v24
	s_nop 0
	v_permlane32_swap_b32_e32 v26, v27
	v_cvt_pk_bf16_f32 v23, v20, v23
	v_mul_f32_e32 v20, v68, v1
	v_lshlrev_b32_e32 v24, 16, v28
	v_add_f32_e32 v26, v26, v27
	v_mul_f32_e32 v20, v20, v24
	v_mul_f32_e32 v24, v69, v1
	v_and_b32_e32 v25, 0xffff0000, v28
	v_div_scale_f32 v27, s[0:1], v26, v26, 1.0
	v_mul_f32_e32 v24, v24, v25
	v_rcp_f32_e32 v28, v27
	v_cvt_pk_bf16_f32 v24, v20, v24
	v_mul_f32_e32 v20, v70, v1
	v_lshlrev_b32_e32 v25, 16, v29
	v_mul_f32_e32 v20, v20, v25
	v_mul_f32_e32 v1, v71, v1
	v_and_b32_e32 v25, 0xffff0000, v29
	v_mul_f32_e32 v1, v1, v25
	v_cvt_pk_bf16_f32 v25, v20, v1
	v_fma_f32 v1, -v27, v28, 1.0
	v_fmac_f32_e32 v28, v1, v28
	v_div_scale_f32 v1, vcc, 1.0, v26, 1.0
	v_mul_f32_e32 v20, v1, v28
	global_store_dwordx4 v[38:39], v[22:25], off offset:1088
	s_nop 1
	v_fma_f32 v22, -v27, v20, v1
	v_fmac_f32_e32 v20, v22, v28
	v_fma_f32 v1, -v27, v20, v1
	v_div_fmas_f32 v1, v1, v28, v20
	v_or_b32_e32 v20, s54, v40
	v_lshlrev_b64 v[22:23], 11, v[20:21]
	v_div_fixup_f32 v1, v1, v26, 1.0
	v_lshl_add_u64 v[22:23], s[48:49], 0, v[22:23]
	v_lshl_add_u64 v[26:27], v[22:23], 0, v[18:19]
	v_mul_f32_e32 v20, v64, v1
	s_waitcnt vmcnt(7)
	v_lshlrev_b32_e32 v22, 16, v30
	v_mul_f32_e32 v20, v20, v22
	v_mul_f32_e32 v22, v65, v1
	v_and_b32_e32 v23, 0xffff0000, v30
	v_mul_f32_e32 v22, v22, v23
	v_cvt_pk_bf16_f32 v22, v20, v22
	v_mul_f32_e32 v20, v66, v1
	v_lshlrev_b32_e32 v23, 16, v31
	v_mul_f32_e32 v20, v20, v23
	v_mul_f32_e32 v23, v67, v1
	v_and_b32_e32 v24, 0xffff0000, v31
	v_mul_f32_e32 v23, v23, v24
	v_cvt_pk_bf16_f32 v23, v20, v23
	v_mul_f32_e32 v20, v60, v1
	v_lshlrev_b32_e32 v24, 16, v32
	v_mul_f32_e32 v20, v20, v24
	v_mul_f32_e32 v24, v61, v1
	v_and_b32_e32 v25, 0xffff0000, v32
	v_mul_f32_e32 v24, v24, v25
	v_cvt_pk_bf16_f32 v24, v20, v24
	v_mul_f32_e32 v20, v62, v1
	v_lshlrev_b32_e32 v25, 16, v33
	v_mul_f32_e32 v20, v20, v25
	v_mul_f32_e32 v25, v63, v1
	v_and_b32_e32 v28, 0xffff0000, v33
	v_mul_f32_e32 v25, v25, v28
	v_cvt_pk_bf16_f32 v25, v20, v25
	global_store_dwordx4 v[26:27], v[22:25], off offset:1024
	v_mul_f32_e32 v20, v56, v1
	v_mov_b32_e32 v28, v224
	s_waitcnt vmcnt(7)
	v_lshlrev_b32_e32 v22, 16, v34
	v_mul_f32_e32 v20, v20, v22
	v_mul_f32_e32 v22, v57, v1
	v_and_b32_e32 v23, 0xffff0000, v34
	v_mul_f32_e32 v22, v22, v23
	v_permlane16_swap_b32_e32 v224, v28
	v_cvt_pk_bf16_f32 v22, v20, v22
	v_mul_f32_e32 v20, v58, v1
	v_lshlrev_b32_e32 v23, 16, v35
	v_add_f32_e32 v28, v224, v28
	v_mul_f32_e32 v20, v20, v23
	v_mul_f32_e32 v23, v59, v1
	v_and_b32_e32 v24, 0xffff0000, v35
	v_mov_b32_e32 v29, v28
	v_mul_f32_e32 v23, v23, v24
	s_nop 0
	v_permlane32_swap_b32_e32 v28, v29
	v_cvt_pk_bf16_f32 v23, v20, v23
	v_mul_f32_e32 v20, v52, v1
	v_lshlrev_b32_e32 v24, 16, v36
	v_add_f32_e32 v28, v28, v29
	v_mul_f32_e32 v20, v20, v24
	v_mul_f32_e32 v24, v53, v1
	v_and_b32_e32 v25, 0xffff0000, v36
	v_div_scale_f32 v29, s[0:1], v28, v28, 1.0
	v_mul_f32_e32 v24, v24, v25
	v_rcp_f32_e32 v30, v29
	v_cvt_pk_bf16_f32 v24, v20, v24
	v_mul_f32_e32 v20, v54, v1
	v_lshlrev_b32_e32 v25, 16, v37
	v_mul_f32_e32 v20, v20, v25
	v_mul_f32_e32 v1, v55, v1
	v_and_b32_e32 v25, 0xffff0000, v37
	v_mul_f32_e32 v1, v1, v25
	v_cvt_pk_bf16_f32 v25, v20, v1
	v_fma_f32 v1, -v29, v30, 1.0
	v_fmac_f32_e32 v30, v1, v30
	v_div_scale_f32 v1, vcc, 1.0, v28, 1.0
	v_mul_f32_e32 v20, v1, v30
	global_store_dwordx4 v[26:27], v[22:25], off offset:1088
	s_nop 1
	v_fma_f32 v22, -v29, v20, v1
	v_fmac_f32_e32 v20, v22, v30
	v_fma_f32 v1, -v29, v20, v1
	v_div_fmas_f32 v1, v1, v30, v20
	v_div_fixup_f32 v1, v1, v28, 1.0
	v_or_b32_e32 v20, s50, v40
	v_lshlrev_b64 v[22:23], 11, v[20:21]
	v_mul_f32_e32 v20, v128, v1
	s_waitcnt vmcnt(7)
	v_lshlrev_b32_e32 v24, 16, v14
	v_mul_f32_e32 v20, v20, v24
	v_mul_f32_e32 v24, v129, v1
	v_and_b32_e32 v14, 0xffff0000, v14
	v_mul_f32_e32 v14, v24, v14
	v_cvt_pk_bf16_f32 v14, v20, v14
	v_mul_f32_e32 v20, v130, v1
	v_lshlrev_b32_e32 v24, 16, v15
	v_mul_f32_e32 v20, v20, v24
	v_mul_f32_e32 v24, v131, v1
	v_and_b32_e32 v15, 0xffff0000, v15
	v_mul_f32_e32 v15, v24, v15
	v_cvt_pk_bf16_f32 v15, v20, v15
	v_mul_f32_e32 v20, v124, v1
	v_lshlrev_b32_e32 v24, 16, v16
	v_mul_f32_e32 v20, v20, v24
	v_mul_f32_e32 v24, v125, v1
	v_and_b32_e32 v16, 0xffff0000, v16
	v_mul_f32_e32 v16, v24, v16
	v_cvt_pk_bf16_f32 v16, v20, v16
	v_mul_f32_e32 v20, v126, v1
	v_lshlrev_b32_e32 v24, 16, v17
	v_lshl_add_u64 v[22:23], s[48:49], 0, v[22:23]
	v_mul_f32_e32 v20, v20, v24
	v_mul_f32_e32 v24, v127, v1
	v_and_b32_e32 v17, 0xffff0000, v17
	v_lshl_add_u64 v[22:23], v[22:23], 0, v[18:19]
	v_mul_f32_e32 v17, v24, v17
	v_cvt_pk_bf16_f32 v17, v20, v17
	global_store_dwordx4 v[22:23], v[14:17], off offset:1024
	v_or_b32_e32 v20, s56, v40
	s_nop 0
	v_mul_f32_e32 v14, v120, v1
	s_waitcnt vmcnt(7)
	v_lshlrev_b32_e32 v15, 16, v10
	v_mul_f32_e32 v14, v14, v15
	v_mul_f32_e32 v15, v121, v1
	v_and_b32_e32 v10, 0xffff0000, v10
	v_mul_f32_e32 v10, v15, v10
	v_cvt_pk_bf16_f32 v10, v14, v10
	v_mul_f32_e32 v14, v122, v1
	v_lshlrev_b32_e32 v15, 16, v11
	v_mul_f32_e32 v14, v14, v15
	v_mul_f32_e32 v15, v123, v1
	v_and_b32_e32 v11, 0xffff0000, v11
	v_mul_f32_e32 v11, v15, v11
	v_cvt_pk_bf16_f32 v11, v14, v11
	v_mul_f32_e32 v14, v116, v1
	v_lshlrev_b32_e32 v15, 16, v12
	v_mul_f32_e32 v14, v14, v15
	v_mul_f32_e32 v15, v117, v1
	v_and_b32_e32 v12, 0xffff0000, v12
	v_mul_f32_e32 v12, v15, v12
	v_cvt_pk_bf16_f32 v12, v14, v12
	v_mul_f32_e32 v14, v118, v1
	v_lshlrev_b32_e32 v15, 16, v13
	v_mul_f32_e32 v14, v14, v15
	v_mov_b32_e32 v15, v225
	s_nop 1
	v_permlane16_swap_b32_e32 v225, v15
	v_add_f32_e32 v15, v225, v15
	v_mov_b32_e32 v16, v15
	s_nop 1
	v_permlane32_swap_b32_e32 v15, v16
	v_add_f32_e32 v15, v15, v16
	v_div_scale_f32 v16, s[0:1], v15, v15, 1.0
	v_rcp_f32_e32 v17, v16
	v_mul_f32_e32 v1, v119, v1
	v_and_b32_e32 v13, 0xffff0000, v13
	v_mul_f32_e32 v1, v1, v13
	v_cvt_pk_bf16_f32 v13, v14, v1
	v_fma_f32 v1, -v16, v17, 1.0
	v_fmac_f32_e32 v17, v1, v17
	v_div_scale_f32 v1, vcc, 1.0, v15, 1.0
	global_store_dwordx4 v[22:23], v[10:13], off offset:1088
	s_mul_i32 s0, s71, s66
	s_add_i32 s4, s0, s65
	v_mul_f32_e32 v10, v1, v17
	v_fma_f32 v11, -v16, v10, v1
	v_fmac_f32_e32 v10, v11, v17
	v_fma_f32 v1, -v16, v10, v1
	v_div_fmas_f32 v1, v1, v17, v10
	v_div_fixup_f32 v1, v1, v15, 1.0
	v_mul_f32_e32 v12, v112, v1
	s_waitcnt vmcnt(7)
	v_lshlrev_b32_e32 v13, 16, v6
	v_mul_f32_e32 v12, v12, v13
	v_mul_f32_e32 v13, v113, v1
	v_and_b32_e32 v6, 0xffff0000, v6
	v_mul_f32_e32 v6, v13, v6
	v_cvt_pk_bf16_f32 v6, v12, v6
	v_mul_f32_e32 v12, v114, v1
	v_lshlrev_b32_e32 v13, 16, v7
	v_mul_f32_e32 v12, v12, v13
	v_mul_f32_e32 v13, v115, v1
	v_and_b32_e32 v7, 0xffff0000, v7
	v_mul_f32_e32 v7, v13, v7
	v_cvt_pk_bf16_f32 v7, v12, v7
	v_mul_f32_e32 v12, v108, v1
	v_lshlrev_b32_e32 v13, 16, v8
	v_mul_f32_e32 v12, v12, v13
	v_mul_f32_e32 v13, v109, v1
	v_and_b32_e32 v8, 0xffff0000, v8
	v_mul_f32_e32 v8, v13, v8
	v_lshlrev_b64 v[10:11], 11, v[20:21]
	v_cvt_pk_bf16_f32 v8, v12, v8
	v_mul_f32_e32 v12, v110, v1
	v_lshlrev_b32_e32 v13, 16, v9
	v_lshl_add_u64 v[10:11], s[48:49], 0, v[10:11]
	v_mul_f32_e32 v12, v12, v13
	v_mul_f32_e32 v13, v111, v1
	v_and_b32_e32 v9, 0xffff0000, v9
	v_lshl_add_u64 v[10:11], v[10:11], 0, v[18:19]
	v_mul_f32_e32 v9, v13, v9
	v_cvt_pk_bf16_f32 v9, v12, v9
	global_store_dwordx4 v[10:11], v[6:9], off offset:1024
	s_ashr_i32 s0, s4, 1
	s_and_b32 s0, s0, -8
	v_mul_f32_e32 v6, v104, v1
	s_waitcnt vmcnt(7)
	v_lshlrev_b32_e32 v7, 16, v2
	v_mul_f32_e32 v6, v6, v7
	v_mul_f32_e32 v7, v105, v1
	v_and_b32_e32 v2, 0xffff0000, v2
	v_mul_f32_e32 v2, v7, v2
	v_cvt_pk_bf16_f32 v2, v6, v2
	v_mul_f32_e32 v6, v106, v1
	v_lshlrev_b32_e32 v7, 16, v3
	v_mul_f32_e32 v6, v6, v7
	v_mul_f32_e32 v7, v107, v1
	v_and_b32_e32 v3, 0xffff0000, v3
	v_mul_f32_e32 v3, v7, v3
	v_cvt_pk_bf16_f32 v3, v6, v3
	v_mul_f32_e32 v6, v100, v1
	v_lshlrev_b32_e32 v7, 16, v4
	v_mul_f32_e32 v6, v6, v7
	v_mul_f32_e32 v7, v101, v1
	v_and_b32_e32 v4, 0xffff0000, v4
	v_mul_f32_e32 v4, v7, v4
	s_or_b32 s0, s0, s64
	v_cvt_pk_bf16_f32 v4, v6, v4
	v_mul_f32_e32 v6, v102, v1
	v_lshlrev_b32_e32 v7, 16, v5
	v_mul_f32_e32 v1, v103, v1
	v_and_b32_e32 v5, 0xffff0000, v5
	s_cmp_gt_i32 s0, 63
	v_mul_f32_e32 v6, v6, v7
	v_mul_f32_e32 v1, v1, v5
	v_cvt_pk_bf16_f32 v5, v6, v1
	global_store_dwordx4 v[10:11], v[2:5], off offset:1088
	s_cbranch_scc1 .LBB0_546

.Latt_dk16:
	s_add_u32 s95, s95, 0x20000
	s_add_u32 s92, s92, 0x100
	s_sub_i32 s63, s63, 2
	s_lshl_b32 s20, s60, 13
	s_add_u32 s23, s20, 0x8000
	s_add_u32 s33, s20, 0xa000
	v_add_u32_e32 v251, s23, v233
	v_add_u32_e32 v253, s33, v234
	ds_read_b128 v[48:51], v251 offset:0
	ds_read_b128 v[40:43], v251 offset:4096
	ds_read_b128 v[44:47], v251 offset:2048
	ds_read_b128 v[36:39], v251 offset:6144
	ds_read_b128 v[16:19], v253 offset:0
	ds_read_b128 v[12:15], v253 offset:2048
	ds_read_b128 v[8:11], v253 offset:4096
	ds_read_b128 v[4:7], v253 offset:6144
	v_mfma_f32_16x16x32_bf16 v[188:191], v[176:179], v[156:159], v[80:83]
	v_mfma_f32_16x16x32_bf16 v[192:195], v[168:171], v[156:159], v[84:87]
	v_mfma_f32_16x16x32_bf16 v[188:191], v[172:175], v[160:163], v[188:191]
	v_mfma_f32_16x16x32_bf16 v[192:195], v[164:167], v[160:163], v[192:195]
	s_nop 6
	v_exp_f32_e32 v188, v188
	v_exp_f32_e32 v189, v189
	v_exp_f32_e32 v190, v190
	v_exp_f32_e32 v191, v191
	v_exp_f32_e32 v192, v192
	v_exp_f32_e32 v193, v193
	v_exp_f32_e32 v194, v194
	v_exp_f32_e32 v195, v195
	v_cvt_pk_bf16_f32 v246, v188, v189
	v_cvt_pk_bf16_f32 v247, v190, v191
	v_cvt_pk_bf16_f32 v248, v192, v193
	v_cvt_pk_bf16_f32 v249, v194, v195
	v_add_f32_e32 v188, v188, v189
	v_add_f32_e32 v190, v190, v191
	v_add_f32_e32 v192, v192, v193
	v_add_f32_e32 v194, v194, v195
	v_add_f32_e32 v188, v188, v190
	v_add_f32_e32 v192, v192, v194
	v_add_f32_e32 v188, v188, v192
	v_add_f32_e32 v225, v225, v188
	v_mfma_f32_16x16x32_bf16 v[112:115], v[32:35], v[246:249], v[112:115]
	v_mfma_f32_16x16x32_bf16 v[108:111], v[28:31], v[246:249], v[108:111]
	v_mfma_f32_16x16x32_bf16 v[104:107], v[24:27], v[246:249], v[104:107]
	v_mfma_f32_16x16x32_bf16 v[100:103], v[20:23], v[246:249], v[100:103]
	v_add_u32_e32 v240, 0x100, v240
	s_sub_u32 s91, 8, s60
	v_and_or_b32 v188, v226, 15, s69
	v_or_b32_e32 v188, s74, v188
	v_mov_b32_e32 v189, s73
	v_ashrrev_i32_e32 v190, 1, v226
	v_and_b32_e32 v190, -8, v190
	v_ashrrev_i32_e32 v191, 31, v190
	v_lshlrev_b64 v[190:191], 1, v[190:191]
	v_lshl_add_u64 v[190:191], s[46:47], 0, v[190:191]
	v_lshl_add_u64 v[192:193], v[188:189], 0, s[36:37]
	v_lshlrev_b64 v[192:193], 10, v[192:193]
	v_lshl_add_u64 v[192:193], v[190:191], 0, v[192:193]
	global_load_dwordx4 v[204:207], v[192:193], off
	global_load_dwordx4 v[208:211], v[192:193], off offset:64
	v_lshl_add_u64 v[192:193], v[188:189], 0, s[54:55]
	v_lshlrev_b64 v[192:193], 10, v[192:193]
	v_lshl_add_u64 v[192:193], v[190:191], 0, v[192:193]
	global_load_dwordx4 v[212:215], v[192:193], off
	global_load_dwordx4 v[242:245], v[192:193], off offset:64
	v_lshl_add_u64 v[192:193], v[188:189], 0, s[50:51]
	v_lshlrev_b64 v[192:193], 10, v[192:193]
	v_lshl_add_u64 v[192:193], v[190:191], 0, v[192:193]
	global_load_dwordx4 v[180:183], v[192:193], off
	global_load_dwordx4 v[184:187], v[192:193], off offset:64
	v_lshl_add_u64 v[192:193], v[188:189], 0, s[56:57]
	v_lshlrev_b64 v[192:193], 10, v[192:193]
	v_lshl_add_u64 v[192:193], v[190:191], 0, v[192:193]
	global_load_dwordx4 v[80:83], v[192:193], off
	global_load_dwordx4 v[84:87], v[192:193], off offset:64
	s_branch .Latt_CB

.Latt_we21:
	v_mfma_f32_16x16x32_bf16 v[188:191], v[48:51], v[156:159], v[204:207]
	v_mfma_f32_16x16x32_bf16 v[192:195], v[40:43], v[156:159], v[208:211]
	v_mfma_f32_16x16x32_bf16 v[188:191], v[44:47], v[160:163], v[188:191]
	v_mfma_f32_16x16x32_bf16 v[192:195], v[36:39], v[160:163], v[192:195]
	ds_read2_b32 v[204:205], v240 offset0:0 offset1:1
	ds_read2_b32 v[206:207], v240 offset0:2 offset1:3
	ds_read2_b32 v[208:209], v240 offset0:4 offset1:5
	ds_read2_b32 v[210:211], v240 offset0:6 offset1:7
	v_mfma_f32_16x16x32_bf16 v[196:199], v[48:51], v[148:151], v[212:215]
	v_mfma_f32_16x16x32_bf16 v[200:203], v[40:43], v[148:151], v[242:245]
	v_mfma_f32_16x16x32_bf16 v[196:199], v[44:47], v[152:155], v[196:199]
	v_mfma_f32_16x16x32_bf16 v[200:203], v[36:39], v[152:155], v[200:203]
	v_exp_f32_e32 v188, v188
	v_exp_f32_e32 v189, v189
	v_exp_f32_e32 v190, v190
	v_exp_f32_e32 v191, v191
	v_exp_f32_e32 v192, v192
	v_exp_f32_e32 v193, v193
	v_exp_f32_e32 v194, v194
	v_exp_f32_e32 v195, v195
	v_cvt_pk_bf16_f32 v246, v188, v189
	v_cvt_pk_bf16_f32 v247, v190, v191
	v_cvt_pk_bf16_f32 v248, v192, v193
	v_cvt_pk_bf16_f32 v249, v194, v195
	v_add_f32_e32 v188, v188, v189
	v_add_f32_e32 v190, v190, v191
	v_add_f32_e32 v192, v192, v193
	v_add_f32_e32 v194, v194, v195
	v_add_f32_e32 v188, v188, v190
	v_add_f32_e32 v192, v192, v194
	v_add_f32_e32 v188, v188, v192
	v_add_f32_e32 v225, v225, v188
	v_mfma_f32_16x16x32_bf16 v[188:191], v[48:51], v[140:143], v[180:183]
	v_mfma_f32_16x16x32_bf16 v[192:195], v[40:43], v[140:143], v[184:187]
	v_mfma_f32_16x16x32_bf16 v[188:191], v[44:47], v[144:147], v[188:191]
	v_mfma_f32_16x16x32_bf16 v[192:195], v[36:39], v[144:147], v[192:195]
	v_exp_f32_e32 v196, v196
	v_exp_f32_e32 v197, v197
	v_exp_f32_e32 v198, v198
	v_exp_f32_e32 v199, v199
	v_mfma_f32_16x16x32_bf16 v[112:115], v[16:19], v[246:249], v[112:115]
	v_exp_f32_e32 v200, v200
	v_exp_f32_e32 v201, v201
	v_exp_f32_e32 v202, v202
	v_exp_f32_e32 v203, v203
	v_mfma_f32_16x16x32_bf16 v[108:111], v[12:15], v[246:249], v[108:111]
	v_cvt_pk_bf16_f32 v92, v196, v197
	v_cvt_pk_bf16_f32 v93, v198, v199
	v_cvt_pk_bf16_f32 v94, v200, v201
	v_cvt_pk_bf16_f32 v95, v202, v203
	v_mfma_f32_16x16x32_bf16 v[104:107], v[8:11], v[246:249], v[104:107]
	v_add_f32_e32 v196, v196, v197
	v_add_f32_e32 v198, v198, v199
	v_add_f32_e32 v200, v200, v201
	v_add_f32_e32 v202, v202, v203
	v_mfma_f32_16x16x32_bf16 v[100:103], v[4:7], v[246:249], v[100:103]
	v_add_f32_e32 v196, v196, v198
	v_add_f32_e32 v200, v200, v202
	v_add_f32_e32 v196, v196, v200
	v_add_f32_e32 v224, v224, v196
	v_mfma_f32_16x16x32_bf16 v[196:199], v[48:51], v[132:135], v[80:83]
	v_mfma_f32_16x16x32_bf16 v[200:203], v[40:43], v[132:135], v[84:87]
	v_mfma_f32_16x16x32_bf16 v[196:199], v[44:47], v[136:139], v[196:199]
	v_mfma_f32_16x16x32_bf16 v[200:203], v[36:39], v[136:139], v[200:203]
	v_exp_f32_e32 v188, v188
	v_exp_f32_e32 v189, v189
	v_exp_f32_e32 v190, v190
	v_exp_f32_e32 v191, v191
	v_mfma_f32_16x16x32_bf16 v[128:131], v[16:19], v[92:95], v[128:131]
	v_exp_f32_e32 v192, v192
	v_exp_f32_e32 v193, v193
	v_exp_f32_e32 v194, v194
	v_exp_f32_e32 v195, v195
	v_mfma_f32_16x16x32_bf16 v[124:127], v[12:15], v[92:95], v[124:127]
	v_cvt_pk_bf16_f32 v246, v188, v189
	v_cvt_pk_bf16_f32 v247, v190, v191
	v_cvt_pk_bf16_f32 v248, v192, v193
	v_cvt_pk_bf16_f32 v249, v194, v195
	v_mfma_f32_16x16x32_bf16 v[120:123], v[8:11], v[92:95], v[120:123]
	v_add_f32_e32 v188, v188, v189
	v_add_f32_e32 v190, v190, v191
	v_add_f32_e32 v192, v192, v193
	v_add_f32_e32 v194, v194, v195
	v_mfma_f32_16x16x32_bf16 v[116:119], v[4:7], v[92:95], v[116:119]
	v_add_f32_e32 v188, v188, v190
	v_add_f32_e32 v192, v192, v194
	v_add_f32_e32 v188, v188, v192
	v_add_f32_e32 v223, v223, v188
	v_exp_f32_e32 v196, v196
	v_exp_f32_e32 v197, v197
	v_exp_f32_e32 v198, v198
	v_exp_f32_e32 v199, v199
	v_mfma_f32_16x16x32_bf16 v[64:67], v[16:19], v[246:249], v[64:67]
	v_exp_f32_e32 v200, v200
	v_exp_f32_e32 v201, v201
	v_exp_f32_e32 v202, v202
	v_exp_f32_e32 v203, v203
	v_mfma_f32_16x16x32_bf16 v[60:63], v[12:15], v[246:249], v[60:63]
	v_cvt_pk_bf16_f32 v92, v196, v197
	v_cvt_pk_bf16_f32 v93, v198, v199
	v_cvt_pk_bf16_f32 v94, v200, v201
	v_cvt_pk_bf16_f32 v95, v202, v203
	v_mfma_f32_16x16x32_bf16 v[56:59], v[8:11], v[246:249], v[56:59]
	v_add_f32_e32 v196, v196, v197
	v_add_f32_e32 v198, v198, v199
	v_add_f32_e32 v200, v200, v201
	v_add_f32_e32 v202, v202, v203
	v_mfma_f32_16x16x32_bf16 v[52:55], v[4:7], v[246:249], v[52:55]
	v_add_f32_e32 v196, v196, v198
	v_add_f32_e32 v200, v200, v202
	v_add_f32_e32 v196, v196, v200
	v_add_f32_e32 v222, v222, v196
	s_waitcnt lgkmcnt(0)
	v_sub_f32_e32 v204, v204, v239
	v_sub_f32_e32 v205, v205, v239
	v_sub_f32_e32 v206, v206, v239
	v_mfma_f32_16x16x32_bf16 v[96:99], v[16:19], v[92:95], v[96:99]
	v_sub_f32_e32 v207, v207, v239
	v_sub_f32_e32 v208, v208, v239
	v_sub_f32_e32 v209, v209, v239
	v_mfma_f32_16x16x32_bf16 v[88:91], v[12:15], v[92:95], v[88:91]
	v_sub_f32_e32 v210, v210, v239
	v_sub_f32_e32 v211, v211, v239
	v_cndmask_b32_e64 v204, v238, v204, s[0:1]
	v_mfma_f32_16x16x32_bf16 v[72:75], v[8:11], v[92:95], v[72:75]
	v_cndmask_b32_e64 v205, v238, v205, s[6:7]
	v_cndmask_b32_e64 v206, v238, v206, s[8:9]
	v_cndmask_b32_e64 v207, v238, v207, s[10:11]
	v_mfma_f32_16x16x32_bf16 v[68:71], v[4:7], v[92:95], v[68:71]
	v_cndmask_b32_e64 v208, v238, v208, s[12:13]
	v_cndmask_b32_e64 v209, v238, v209, s[14:15]
	v_cndmask_b32_e64 v210, v238, v210, s[16:17]
	v_cndmask_b32_e64 v211, v238, v211, s[18:19]
	v_add_u32_e32 v240, 0x100, v240
	s_sub_u32 s91, s91, 1
	s_cmp_lg_u32 s91, 0
	s_cbranch_scc1 .Latt_F0
	s_sub_u32 s91, 8, s60
	v_and_or_b32 v188, v226, 15, s69
	v_or_b32_e32 v188, s74, v188
	v_mov_b32_e32 v189, s73
	v_ashrrev_i32_e32 v190, 1, v226
	v_and_b32_e32 v190, -8, v190
	v_ashrrev_i32_e32 v191, 31, v190
	v_lshlrev_b64 v[190:191], 1, v[190:191]
	v_lshl_add_u64 v[190:191], s[46:47], 0, v[190:191]
	v_lshl_add_u64 v[192:193], v[188:189], 0, s[36:37]
	v_lshlrev_b64 v[192:193], 10, v[192:193]
	v_lshl_add_u64 v[192:193], v[190:191], 0, v[192:193]
	global_load_dwordx4 v[204:207], v[192:193], off
	global_load_dwordx4 v[208:211], v[192:193], off offset:64
	v_lshl_add_u64 v[192:193], v[188:189], 0, s[54:55]
	v_lshlrev_b64 v[192:193], 10, v[192:193]
	v_lshl_add_u64 v[192:193], v[190:191], 0, v[192:193]
	global_load_dwordx4 v[212:215], v[192:193], off
	global_load_dwordx4 v[242:245], v[192:193], off offset:64
	v_lshl_add_u64 v[192:193], v[188:189], 0, s[50:51]
	v_lshlrev_b64 v[192:193], 10, v[192:193]
	v_lshl_add_u64 v[192:193], v[190:191], 0, v[192:193]
	global_load_dwordx4 v[180:183], v[192:193], off
	global_load_dwordx4 v[184:187], v[192:193], off offset:64
	v_lshl_add_u64 v[192:193], v[188:189], 0, s[56:57]
	v_lshlrev_b64 v[192:193], 10, v[192:193]
	v_lshl_add_u64 v[192:193], v[190:191], 0, v[192:193]
	global_load_dwordx4 v[80:83], v[192:193], off
	global_load_dwordx4 v[84:87], v[192:193], off offset:64
.Latt_CA:
	s_waitcnt lgkmcnt(0)
	s_waitcnt vmcnt(8)
	s_cmp_gt_i32 s63, -2
	s_cbranch_scc0 .Latt_eb22
	s_barrier

.Latt_cdone:
	s_nop 7
	s_cmp_eq_u32 s76, 8
	s_cbranch_scc0 .Latt_end
	s_waitcnt lgkmcnt(0)
	s_waitcnt vmcnt(8)
	s_cmp_gt_i32 s63, -2
	s_cbranch_scc0 .Latt_eb23
	s_barrier
.Latt_eb23:
	s_sub_i32 s63, s63, 2
	s_waitcnt lgkmcnt(0)
	s_waitcnt vmcnt(8)
	s_cmp_gt_i32 s63, -2
	s_cbranch_scc0 .Latt_eb24
	s_barrier
